# RWKV scan step 3: v_mov copy of the v scalar replaced by an op_sel high-half broadcast (reads reordered before the overwrite)
# baseline (speedup 1.0000x reference)
; __device__ __forceinline__ void phase_rwkv(KP P, int l_, unsigned char* shm) {
;     ...
;                 f32x4 Aw0, Aw1, Akk0, Akk1, Ab0, Ab1, Ak0, Ak1, Ar0, Ar1; float Ava, Avb;
;                 f32x4 Bw0, Bw1, Bkk0, Bkk1, Bb0, Bb1, Bk0, Bk1, Br0, Br1; float Bva, Bvb;
;                 RW_LD(A, 0);
; #pragma unroll 2
;                 for (int tl = 0; tl < T; tl += 2) {
;                     RW_LD(B, tl + 1);
;                     RW_STEP(A, tl);
;                     RW_LD(A, tl + 2);
;                     RW_STEP(B, tl + 1);
;                 }
.LBB0_2517:
	v_pk_mul_f32 v[110:111], v[40:41], v[92:93]
	v_pk_mul_f32 v[40:41], v[40:41], v[100:101]
	v_pk_fma_f32 v[110:111], v[38:39], v[90:91], v[110:111]
	v_pk_fma_f32 v[38:39], v[38:39], v[98:99], v[40:41]
	v_pk_fma_f32 v[40:41], v[36:37], v[96:97], v[110:111]
	v_pk_fma_f32 v[36:37], v[36:37], v[104:105], v[38:39]
	v_pk_fma_f32 v[40:41], v[34:35], v[94:95], v[40:41]
	v_pk_fma_f32 v[34:35], v[34:35], v[102:103], v[36:37]
	v_add_f32_e32 v36, v40, v41
	v_add_f32_e32 v34, v34, v35
	ds_read_b128 v[62:65], v235
	v_add_f32_dpp v35, v36, v36 quad_perm:[1,0,3,2] row_mask:0xf bank_mask:0xf bound_ctrl:1
	v_add_f32_dpp v34, v34, v34 quad_perm:[1,0,3,2] row_mask:0xf bank_mask:0xf bound_ctrl:1
	ds_read_b128 v[50:53], v235 offset:16
	ds_read_b128 v[78:81], v235 offset:8192
	ds_read_b128 v[74:77], v235 offset:8208
	ds_read_b128 v[66:69], v235 offset:16384
	ds_read_b128 v[54:57], v235 offset:16400
	ds_read_b128 v[70:73], v235 offset:24576
	ds_read_b128 v[58:61], v235 offset:24592
	ds_read_b128 v[46:49], v235 offset:32768
	ds_read_b128 v[42:45], v235 offset:32784
	v_add_f32_dpp v35, v35, v35 quad_perm:[2,3,0,1] row_mask:0xf bank_mask:0xf bound_ctrl:1
	v_add_f32_dpp v36, v34, v34 quad_perm:[2,3,0,1] row_mask:0xf bank_mask:0xf bound_ctrl:1
	v_add_u32_e32 v186, s43, v252
	v_add_f32_dpp v34, v35, v35 row_half_mirror row_mask:0xf bank_mask:0xf bound_ctrl:1
	v_add_f32_dpp v36, v36, v36 row_half_mirror row_mask:0xf bank_mask:0xf bound_ctrl:1
	v_pk_mul_f32 v[38:39], v[26:27], v[34:35] op_sel_hi:[1,0] neg_lo:[0,1] neg_hi:[0,1]
	v_pk_mul_f32 v[26:27], v[26:27], v[36:37] op_sel_hi:[1,0] neg_lo:[0,1] neg_hi:[0,1]
	v_pk_fma_f32 v[38:39], v[10:11], v[90:91], v[38:39]
	v_pk_fma_f32 v[10:11], v[10:11], v[98:99], v[26:27]
	s_waitcnt lgkmcnt(13)
	v_pk_fma_f32 v[110:111], v[30:31], v[106:107], v[38:39] op_sel_hi:[1,0,1]
	v_pk_fma_f32 v[98:99], v[30:31], v[106:107], v[10:11] op_sel:[0,1,0]
	v_pk_mul_f32 v[10:11], v[28:29], v[34:35] op_sel_hi:[1,0] neg_lo:[0,1] neg_hi:[0,1]
	v_pk_mul_f32 v[170:171], v[28:29], v[36:37] op_sel_hi:[1,0] neg_lo:[0,1] neg_hi:[0,1]
	ds_read2_b32 v[108:109], v186 offset1:32
	v_pk_fma_f32 v[10:11], v[12:13], v[92:93], v[10:11]
	v_pk_fma_f32 v[170:171], v[12:13], v[100:101], v[170:171]
	v_pk_fma_f32 v[92:93], v[32:33], v[106:107], v[10:11] op_sel_hi:[1,0,1]
	v_pk_fma_f32 v[100:101], v[32:33], v[106:107], v[170:171] op_sel:[0,1,0]
	v_pk_mul_f32 v[10:11], v[6:7], v[34:35] op_sel_hi:[1,0] neg_lo:[0,1] neg_hi:[0,1]
	v_pk_mul_f32 v[6:7], v[6:7], v[36:37] op_sel_hi:[1,0] neg_lo:[0,1] neg_hi:[0,1]
	v_pk_fma_f32 v[10:11], v[0:1], v[94:95], v[10:11]
	v_pk_fma_f32 v[0:1], v[0:1], v[102:103], v[6:7]
	s_waitcnt lgkmcnt(13)
	v_pk_fma_f32 v[94:95], v[22:23], v[106:107], v[10:11] op_sel_hi:[1,0,1]
	v_pk_fma_f32 v[102:103], v[22:23], v[106:107], v[0:1] op_sel:[0,1,0]
	v_pk_mul_f32 v[0:1], v[8:9], v[34:35] op_sel_hi:[1,0] neg_lo:[0,1] neg_hi:[0,1]
	v_pk_mul_f32 v[170:171], v[8:9], v[36:37] op_sel_hi:[1,0] neg_lo:[0,1] neg_hi:[0,1]
	v_pk_fma_f32 v[0:1], v[2:3], v[96:97], v[0:1]
	v_pk_fma_f32 v[170:171], v[2:3], v[104:105], v[170:171]
	v_pk_fma_f32 v[96:97], v[24:25], v[106:107], v[0:1] op_sel_hi:[1,0,1]
	v_pk_fma_f32 v[104:105], v[24:25], v[106:107], v[170:171] op_sel:[0,1,0]
	s_waitcnt lgkmcnt(11)
	v_pk_mul_f32 v[2:3], v[20:21], v[100:101]
	v_pk_mul_f32 v[0:1], v[20:21], v[92:93]
	v_pk_fma_f32 v[2:3], v[18:19], v[98:99], v[2:3]
	v_pk_fma_f32 v[0:1], v[18:19], v[110:111], v[0:1]
	v_pk_fma_f32 v[8:9], v[16:17], v[104:105], v[2:3]
	v_pk_fma_f32 v[6:7], v[16:17], v[96:97], v[0:1]
	v_pk_fma_f32 v[8:9], v[14:15], v[102:103], v[8:9]
	v_pk_fma_f32 v[6:7], v[14:15], v[94:95], v[6:7]
	v_add_f32_e32 v158, v8, v9
	v_add_f32_e32 v157, v6, v7
	s_waitcnt lgkmcnt(6)
	v_pk_mul_f32 v[106:107], v[80:81], v[92:93]
	v_pk_mul_f32 v[80:81], v[80:81], v[100:101]
	v_pk_fma_f32 v[106:107], v[78:79], v[110:111], v[106:107]
	v_pk_fma_f32 v[78:79], v[78:79], v[98:99], v[80:81]
	s_waitcnt lgkmcnt(5)
	v_pk_fma_f32 v[80:81], v[76:77], v[96:97], v[106:107]
	v_pk_fma_f32 v[76:77], v[76:77], v[104:105], v[78:79]
	v_pk_fma_f32 v[80:81], v[74:75], v[94:95], v[80:81]
	v_pk_fma_f32 v[74:75], v[74:75], v[102:103], v[76:77]
	v_add_f32_e32 v4, v80, v81
	v_add_f32_e32 v74, v74, v75
	s_waitcnt lgkmcnt(0)
	v_add_f32_dpp v4, v4, v4 quad_perm:[1,0,3,2] row_mask:0xf bank_mask:0xf bound_ctrl:1
	v_add_f32_dpp v74, v74, v74 quad_perm:[1,0,3,2] row_mask:0xf bank_mask:0xf bound_ctrl:1
	ds_read_b128 v[22:25], v235 offset:256
	ds_read_b128 v[10:13], v235 offset:272
	ds_read_b128 v[38:41], v235 offset:8448
	ds_read_b128 v[34:37], v235 offset:8464
	ds_read_b128 v[26:29], v235 offset:16640
	ds_read_b128 v[14:17], v235 offset:16656
	ds_read_b128 v[30:33], v235 offset:24832
	ds_read_b128 v[18:21], v235 offset:24848
	ds_read_b128 v[6:9], v235 offset:33024
	ds_read_b128 v[0:3], v235 offset:33040
	ds_read2_b32 v[90:91], v186 offset0:64 offset1:96
	v_add_f32_dpp v4, v4, v4 quad_perm:[2,3,0,1] row_mask:0xf bank_mask:0xf bound_ctrl:1
	v_add_f32_dpp v74, v74, v74 quad_perm:[2,3,0,1] row_mask:0xf bank_mask:0xf bound_ctrl:1
	s_nop 0
	v_add_f32_dpp v4, v4, v4 row_half_mirror row_mask:0xf bank_mask:0xf bound_ctrl:1
	v_add_f32_dpp v74, v74, v74 row_half_mirror row_mask:0xf bank_mask:0xf bound_ctrl:1
	v_pk_mul_f32 v[78:79], v[66:67], v[4:5] op_sel_hi:[1,0] neg_lo:[0,1] neg_hi:[0,1]
	v_pk_mul_f32 v[66:67], v[66:67], v[74:75] op_sel_hi:[1,0] neg_lo:[0,1] neg_hi:[0,1]
	v_pk_fma_f32 v[78:79], v[62:63], v[110:111], v[78:79]
	v_pk_fma_f32 v[62:63], v[62:63], v[98:99], v[66:67]
	v_pk_fma_f32 v[106:107], v[70:71], v[108:109], v[78:79] op_sel_hi:[1,0,1]
	v_pk_fma_f32 v[98:99], v[70:71], v[108:109], v[62:63] op_sel:[0,1,0]
	v_pk_mul_f32 v[62:63], v[68:69], v[4:5] op_sel_hi:[1,0] neg_lo:[0,1] neg_hi:[0,1]
	v_pk_mul_f32 v[170:171], v[68:69], v[74:75] op_sel_hi:[1,0] neg_lo:[0,1] neg_hi:[0,1]
	v_pk_fma_f32 v[62:63], v[64:65], v[92:93], v[62:63]
	v_pk_fma_f32 v[170:171], v[64:65], v[100:101], v[170:171]
	v_pk_fma_f32 v[110:111], v[72:73], v[108:109], v[62:63] op_sel_hi:[1,0,1]
	v_pk_fma_f32 v[112:113], v[72:73], v[108:109], v[170:171] op_sel:[0,1,0]
	v_pk_mul_f32 v[62:63], v[54:55], v[4:5] op_sel_hi:[1,0] neg_lo:[0,1] neg_hi:[0,1]
	v_pk_mul_f32 v[54:55], v[54:55], v[74:75] op_sel_hi:[1,0] neg_lo:[0,1] neg_hi:[0,1]
	v_pk_fma_f32 v[62:63], v[50:51], v[94:95], v[62:63]
	v_pk_fma_f32 v[50:51], v[50:51], v[102:103], v[54:55]
	v_pk_fma_f32 v[114:115], v[58:59], v[108:109], v[62:63] op_sel_hi:[1,0,1]
	v_pk_fma_f32 v[116:117], v[58:59], v[108:109], v[50:51] op_sel:[0,1,0]
	v_pk_mul_f32 v[50:51], v[56:57], v[4:5] op_sel_hi:[1,0] neg_lo:[0,1] neg_hi:[0,1]
	v_pk_mul_f32 v[170:171], v[56:57], v[74:75] op_sel_hi:[1,0] neg_lo:[0,1] neg_hi:[0,1]
	v_pk_fma_f32 v[50:51], v[52:53], v[96:97], v[50:51]
	v_pk_fma_f32 v[170:171], v[52:53], v[104:105], v[170:171]
	v_pk_fma_f32 v[118:119], v[60:61], v[108:109], v[50:51] op_sel_hi:[1,0,1]
	v_pk_fma_f32 v[120:121], v[60:61], v[108:109], v[170:171] op_sel:[0,1,0]
	v_pk_mul_f32 v[50:51], v[48:49], v[110:111]
	v_pk_mul_f32 v[48:49], v[48:49], v[112:113]
	v_pk_fma_f32 v[50:51], v[46:47], v[106:107], v[50:51]
	v_pk_fma_f32 v[46:47], v[46:47], v[98:99], v[48:49]
	v_pk_fma_f32 v[48:49], v[44:45], v[118:119], v[50:51]
	v_pk_fma_f32 v[44:45], v[44:45], v[120:121], v[46:47]
	v_pk_fma_f32 v[48:49], v[42:43], v[114:115], v[48:49]
	v_pk_fma_f32 v[42:43], v[42:43], v[116:117], v[44:45]
	v_add_f32_e32 v159, v48, v49
	v_add_f32_e32 v160, v42, v43
	s_waitcnt lgkmcnt(6)
	v_pk_mul_f32 v[92:93], v[40:41], v[110:111]
	v_pk_mul_f32 v[40:41], v[40:41], v[112:113]
	v_pk_fma_f32 v[92:93], v[38:39], v[106:107], v[92:93]
	v_pk_fma_f32 v[38:39], v[38:39], v[98:99], v[40:41]
	s_waitcnt lgkmcnt(5)
	v_pk_fma_f32 v[40:41], v[36:37], v[118:119], v[92:93]
	v_pk_fma_f32 v[36:37], v[36:37], v[120:121], v[38:39]
	v_pk_fma_f32 v[40:41], v[34:35], v[114:115], v[40:41]
	v_pk_fma_f32 v[34:35], v[34:35], v[116:117], v[36:37]
	v_add_f32_e32 v4, v40, v41
	v_add_f32_e32 v34, v34, v35
	s_waitcnt lgkmcnt(0)
	v_add_f32_dpp v4, v4, v4 quad_perm:[1,0,3,2] row_mask:0xf bank_mask:0xf bound_ctrl:1
	v_add_f32_dpp v34, v34, v34 quad_perm:[1,0,3,2] row_mask:0xf bank_mask:0xf bound_ctrl:1
	ds_read_b128 v[62:65], v235 offset:512
	ds_read_b128 v[50:53], v235 offset:528
	ds_read_b128 v[78:81], v235 offset:8704
	ds_read_b128 v[74:77], v235 offset:8720
	ds_read_b128 v[66:69], v235 offset:16896
	ds_read_b128 v[54:57], v235 offset:16912
	ds_read_b128 v[70:73], v235 offset:25088
	ds_read_b128 v[58:61], v235 offset:25104
	ds_read_b128 v[46:49], v235 offset:33280
	ds_read_b128 v[42:45], v235 offset:33296
	ds_read2_b32 v[96:97], v186 offset0:128 offset1:160
	v_add_f32_dpp v4, v4, v4 quad_perm:[2,3,0,1] row_mask:0xf bank_mask:0xf bound_ctrl:1
	v_add_f32_dpp v34, v34, v34 quad_perm:[2,3,0,1] row_mask:0xf bank_mask:0xf bound_ctrl:1
	s_nop 0
	v_add_f32_dpp v4, v4, v4 row_half_mirror row_mask:0xf bank_mask:0xf bound_ctrl:1
	v_add_f32_dpp v34, v34, v34 row_half_mirror row_mask:0xf bank_mask:0xf bound_ctrl:1
	v_pk_mul_f32 v[38:39], v[26:27], v[4:5] op_sel_hi:[1,0] neg_lo:[0,1] neg_hi:[0,1]
	v_pk_mul_f32 v[26:27], v[26:27], v[34:35] op_sel_hi:[1,0] neg_lo:[0,1] neg_hi:[0,1]
	v_pk_fma_f32 v[38:39], v[22:23], v[106:107], v[38:39]
	v_pk_fma_f32 v[22:23], v[22:23], v[98:99], v[26:27]
	v_pk_fma_f32 v[92:93], v[30:31], v[90:91], v[38:39] op_sel_hi:[1,0,1]
	v_pk_fma_f32 v[94:95], v[30:31], v[90:91], v[22:23] op_sel:[0,1,0]
	v_pk_mul_f32 v[22:23], v[28:29], v[4:5] op_sel_hi:[1,0] neg_lo:[0,1] neg_hi:[0,1]
	v_pk_mul_f32 v[170:171], v[28:29], v[34:35] op_sel_hi:[1,0] neg_lo:[0,1] neg_hi:[0,1]
	v_pk_fma_f32 v[22:23], v[24:25], v[110:111], v[22:23]
	v_pk_fma_f32 v[170:171], v[24:25], v[112:113], v[170:171]
	v_pk_fma_f32 v[100:101], v[32:33], v[90:91], v[22:23] op_sel_hi:[1,0,1]
	v_pk_fma_f32 v[102:103], v[32:33], v[90:91], v[170:171] op_sel:[0,1,0]
	v_pk_mul_f32 v[22:23], v[14:15], v[4:5] op_sel_hi:[1,0] neg_lo:[0,1] neg_hi:[0,1]
	v_pk_mul_f32 v[14:15], v[14:15], v[34:35] op_sel_hi:[1,0] neg_lo:[0,1] neg_hi:[0,1]
	v_pk_fma_f32 v[22:23], v[10:11], v[114:115], v[22:23]
	v_pk_fma_f32 v[10:11], v[10:11], v[116:117], v[14:15]
	v_pk_fma_f32 v[104:105], v[18:19], v[90:91], v[22:23] op_sel_hi:[1,0,1]
	v_pk_fma_f32 v[108:109], v[18:19], v[90:91], v[10:11] op_sel:[0,1,0]
	v_pk_mul_f32 v[10:11], v[16:17], v[4:5] op_sel_hi:[1,0] neg_lo:[0,1] neg_hi:[0,1]
	v_pk_mul_f32 v[170:171], v[16:17], v[34:35] op_sel_hi:[1,0] neg_lo:[0,1] neg_hi:[0,1]
	v_pk_fma_f32 v[10:11], v[12:13], v[118:119], v[10:11]
	v_pk_fma_f32 v[170:171], v[12:13], v[120:121], v[170:171]
	v_pk_fma_f32 v[110:111], v[20:21], v[90:91], v[10:11] op_sel_hi:[1,0,1]
	v_pk_fma_f32 v[112:113], v[20:21], v[90:91], v[170:171] op_sel:[0,1,0]
	v_pk_mul_f32 v[10:11], v[8:9], v[100:101]
	v_pk_mul_f32 v[8:9], v[8:9], v[102:103]
	v_pk_fma_f32 v[10:11], v[6:7], v[92:93], v[10:11]
	v_pk_fma_f32 v[6:7], v[6:7], v[94:95], v[8:9]
	v_pk_fma_f32 v[8:9], v[2:3], v[110:111], v[10:11]
	v_pk_fma_f32 v[2:3], v[2:3], v[112:113], v[6:7]
	v_pk_fma_f32 v[8:9], v[0:1], v[104:105], v[8:9]
	v_pk_fma_f32 v[0:1], v[0:1], v[108:109], v[2:3]
	v_add_f32_e32 v161, v8, v9
	v_add_f32_e32 v162, v0, v1
	s_waitcnt lgkmcnt(6)
; __device__ __forceinline__ void phase_rwkv(KP P, int l_, unsigned char* shm) {
;     ...
;                 f32x4 Aw0, Aw1, Akk0, Akk1, Ab0, Ab1, Ak0, Ak1, Ar0, Ar1; float Ava, Avb;
;                 f32x4 Bw0, Bw1, Bkk0, Bkk1, Bb0, Bb1, Bk0, Bk1, Br0, Br1; float Bva, Bvb;
;                 RW_LD(A, 0);
; #pragma unroll 2
;                 for (int tl = 0; tl < T; tl += 2) {
;                     RW_LD(B, tl + 1);
;                     RW_STEP(A, tl);
;                     RW_LD(A, tl + 2);
;                     RW_STEP(B, tl + 1);
;                 }
	v_pk_mul_f32 v[90:91], v[80:81], v[100:101]
	v_pk_mul_f32 v[80:81], v[80:81], v[102:103]
	v_pk_fma_f32 v[90:91], v[78:79], v[92:93], v[90:91]
	v_pk_fma_f32 v[78:79], v[78:79], v[94:95], v[80:81]
	s_waitcnt lgkmcnt(5)
	v_pk_fma_f32 v[80:81], v[76:77], v[110:111], v[90:91]
	v_pk_fma_f32 v[76:77], v[76:77], v[112:113], v[78:79]
	v_pk_fma_f32 v[80:81], v[74:75], v[104:105], v[80:81]
	v_pk_fma_f32 v[74:75], v[74:75], v[108:109], v[76:77]
	v_add_f32_e32 v76, v80, v81
	v_add_f32_e32 v74, v74, v75
	s_waitcnt lgkmcnt(0)
	v_add_f32_dpp v75, v76, v76 quad_perm:[1,0,3,2] row_mask:0xf bank_mask:0xf bound_ctrl:1
	v_add_f32_dpp v74, v74, v74 quad_perm:[1,0,3,2] row_mask:0xf bank_mask:0xf bound_ctrl:1
	ds_read_b128 v[10:13], v235 offset:768
	ds_read_b128 v[0:3], v235 offset:784
	ds_read_b128 v[38:41], v235 offset:8960
	ds_read_b128 v[34:37], v235 offset:8976
	ds_read_b128 v[26:29], v235 offset:17152
	ds_read_b128 v[6:9], v235 offset:17168
	ds_read2_b32 v[106:107], v186 offset0:192 offset1:224
	ds_read_b128 v[30:33], v235 offset:25344
	ds_read_b128 v[22:25], v235 offset:25360
	ds_read_b128 v[18:21], v235 offset:33536
	ds_read_b128 v[14:17], v235 offset:33552
	v_add_f32_dpp v75, v75, v75 quad_perm:[2,3,0,1] row_mask:0xf bank_mask:0xf bound_ctrl:1
	v_add_f32_dpp v76, v74, v74 quad_perm:[2,3,0,1] row_mask:0xf bank_mask:0xf bound_ctrl:1
	s_waitcnt lgkmcnt(4)
	v_add_f32_dpp v74, v75, v75 row_half_mirror row_mask:0xf bank_mask:0xf bound_ctrl:1
	v_add_f32_dpp v76, v76, v76 row_half_mirror row_mask:0xf bank_mask:0xf bound_ctrl:1
	v_pk_mul_f32 v[80:81], v[66:67], v[74:75] op_sel_hi:[1,0] neg_lo:[0,1] neg_hi:[0,1]
	v_pk_mul_f32 v[66:67], v[66:67], v[76:77] op_sel_hi:[1,0] neg_lo:[0,1] neg_hi:[0,1]
	v_pk_fma_f32 v[80:81], v[62:63], v[92:93], v[80:81]
	v_pk_fma_f32 v[62:63], v[62:63], v[94:95], v[66:67]
	v_pk_fma_f32 v[90:91], v[70:71], v[96:97], v[80:81] op_sel_hi:[1,0,1]
	v_pk_fma_f32 v[98:99], v[70:71], v[96:97], v[62:63] op_sel:[0,1,0]
	v_pk_mul_f32 v[62:63], v[68:69], v[74:75] op_sel_hi:[1,0] neg_lo:[0,1] neg_hi:[0,1]
	v_pk_mul_f32 v[170:171], v[68:69], v[76:77] op_sel_hi:[1,0] neg_lo:[0,1] neg_hi:[0,1]
	v_pk_fma_f32 v[62:63], v[64:65], v[100:101], v[62:63]
	v_pk_fma_f32 v[170:171], v[64:65], v[102:103], v[170:171]
	v_pk_fma_f32 v[92:93], v[72:73], v[96:97], v[62:63] op_sel_hi:[1,0,1]
	v_pk_fma_f32 v[100:101], v[72:73], v[96:97], v[170:171] op_sel:[0,1,0]
	v_pk_mul_f32 v[62:63], v[54:55], v[74:75] op_sel_hi:[1,0] neg_lo:[0,1] neg_hi:[0,1]
	v_pk_mul_f32 v[54:55], v[54:55], v[76:77] op_sel_hi:[1,0] neg_lo:[0,1] neg_hi:[0,1]
	v_pk_fma_f32 v[62:63], v[50:51], v[104:105], v[62:63]
	v_pk_fma_f32 v[50:51], v[50:51], v[108:109], v[54:55]
	v_pk_fma_f32 v[94:95], v[58:59], v[96:97], v[62:63] op_sel_hi:[1,0,1]
	v_pk_fma_f32 v[102:103], v[58:59], v[96:97], v[50:51] op_sel:[0,1,0]
	v_pk_mul_f32 v[50:51], v[56:57], v[74:75] op_sel_hi:[1,0] neg_lo:[0,1] neg_hi:[0,1]
	v_pk_mul_f32 v[170:171], v[56:57], v[76:77] op_sel_hi:[1,0] neg_lo:[0,1] neg_hi:[0,1]
	v_pk_fma_f32 v[50:51], v[52:53], v[110:111], v[50:51]
	v_pk_fma_f32 v[170:171], v[52:53], v[112:113], v[170:171]
	v_pk_fma_f32 v[104:105], v[60:61], v[96:97], v[170:171] op_sel:[0,1,0]
	v_pk_fma_f32 v[96:97], v[60:61], v[96:97], v[50:51] op_sel_hi:[1,0,1]
	v_pk_mul_f32 v[50:51], v[48:49], v[92:93]
	v_pk_mul_f32 v[48:49], v[48:49], v[100:101]
	v_pk_fma_f32 v[50:51], v[46:47], v[90:91], v[50:51]
	v_pk_fma_f32 v[46:47], v[46:47], v[98:99], v[48:49]
	v_pk_fma_f32 v[48:49], v[44:45], v[96:97], v[50:51]
	v_pk_fma_f32 v[44:45], v[44:45], v[104:105], v[46:47]
	v_pk_fma_f32 v[48:49], v[42:43], v[94:95], v[48:49]
	v_pk_fma_f32 v[42:43], v[42:43], v[102:103], v[44:45]
	v_add_f32_e32 v163, v48, v49
	v_add_f32_e32 v164, v42, v43
	v_cndmask_b32_e64 v166, v159, v157, s[98:99]
	v_cndmask_b32_e64 v168, v163, v161, s[98:99]
	v_cndmask_b32_e64 v172, v160, v158, s[98:99]
	v_cndmask_b32_e64 v240, v164, v162, s[98:99]
	v_cndmask_b32_e64 v165, v157, v159, s[98:99]
	v_cndmask_b32_e64 v167, v161, v163, s[98:99]
	v_cndmask_b32_e64 v169, v158, v160, s[98:99]
	v_cndmask_b32_e64 v187, v162, v164, s[98:99]
	v_add_f32_dpp v165, v166, v165 quad_perm:[1,0,3,2] row_mask:0xf bank_mask:0xf bound_ctrl:1
	v_add_f32_dpp v167, v168, v167 quad_perm:[1,0,3,2] row_mask:0xf bank_mask:0xf bound_ctrl:1
	v_add_f32_dpp v169, v172, v169 quad_perm:[1,0,3,2] row_mask:0xf bank_mask:0xf bound_ctrl:1
	v_add_f32_dpp v187, v240, v187 quad_perm:[1,0,3,2] row_mask:0xf bank_mask:0xf bound_ctrl:1
	v_cndmask_b32_e64 v166, v167, v165, s[100:101]
	v_cndmask_b32_e64 v172, v187, v169, s[100:101]
	v_cndmask_b32_e64 v165, v165, v167, s[100:101]
	v_cndmask_b32_e64 v169, v169, v187, s[100:101]
	v_add_f32_dpp v165, v166, v165 quad_perm:[2,3,0,1] row_mask:0xf bank_mask:0xf bound_ctrl:1
	v_add_f32_dpp v169, v172, v169 quad_perm:[2,3,0,1] row_mask:0xf bank_mask:0xf bound_ctrl:1
	s_nop 0
	v_add_f32_dpp v165, v165, v165 row_shr:4 row_mask:0xf bank_mask:0xf bound_ctrl:1
	v_add_f32_dpp v169, v169, v169 row_shr:4 row_mask:0xf bank_mask:0xf bound_ctrl:1
	s_mov_b64 s[72:73], exec
	s_mov_b32 exec_lo, 0xf0f0f0f0
	s_mov_b32 exec_hi, 0xf0f0f0f0
	ds_write_b32 v253, v165
	ds_write_b32 v253, v169 offset:128
	s_mov_b64 exec, s[72:73]
	s_branch .LBB0_2516
